# v17 + P30 filter-spectra table loads no longer serialised: removed hipcc per-register WAW-guard vmcnt(0) before each first-half address computation (26 sites)
# speedup vs baseline: 1.0031x; 1.0031x over previous
; template <int M>
; __device__ __forceinline__ void hy_filter_spectra(LAS vf2* X, const int tid_in, const float* hfa, const float* hba, const float* hfb, const float* hbb, vf2* FSa, vf2* FSb) {
;     ...
;     { float va[N / NTHR], vb[N / NTHR];
; #pragma unroll
;         for (int j = 0; j < N / NTHR; ++j) { const int i = tid + NTHR * j; if (i < L) { va[j] = hfa[i]; vb[j] = hfb[i]; } else if (i == L) { va[j] = 0.f; vb[j] = 0.f; } else { va[j] = hba[N - i]; vb[j] = hbb[N - i]; } }
; #pragma unroll
;         for (int j = 0; j < N / NTHR; ++j) { const int i = tid + NTHR * j; X[i + (i >> 4)] = (vf2){va[j], vb[j]}; } }
.LBB0_2766:
	s_andn2_saveexec_b64 s[0:1], s[0:1]
	s_cbranch_execz .LBB0_2768
	v_ashrrev_i32_e32 v61, 31, v60
	v_lshlrev_b64 v[64:65], 2, v[60:61]
	v_lshl_add_u64 v[66:67], s[4:5], 0, v[64:65]
	v_lshl_add_u64 v[64:65], s[58:59], 0, v[64:65]
	global_load_dword v1, v[66:67], off offset:2048
	s_nop 0
	global_load_dword v65, v[64:65], off offset:2048

; template <int M>
; __device__ __forceinline__ void hy_filter_spectra(LAS vf2* X, const int tid_in, const float* hfa, const float* hba, const float* hfb, const float* hbb, vf2* FSa, vf2* FSb) {
;     ...
;         for (int j = 0; j < N / NTHR; ++j) { const int i = tid + NTHR * j; if (i < L) { va[j] = hfa[i]; vb[j] = hfb[i]; } else if (i == L) { va[j] = 0.f; vb[j] = 0.f; } else { va[j] = hba[N - i]; vb[j] = hbb[N - i]; } }
.LBB0_2782:
	s_andn2_saveexec_b64 s[0:1], s[0:1]
	s_cbranch_execz .LBB0_2784
	v_ashrrev_i32_e32 v69, 31, v68
	v_lshlrev_b64 v[70:71], 2, v[68:69]
	v_lshl_add_u64 v[72:73], s[4:5], 0, v[70:71]
	v_lshl_add_u64 v[70:71], s[58:59], 0, v[70:71]
	global_load_dword v3, v[72:73], off
	s_nop 0
	global_load_dword v71, v[70:71], off

; template <int M>
; __device__ __forceinline__ void hy_filter_spectra(LAS vf2* X, const int tid_in, const float* hfa, const float* hba, const float* hfb, const float* hbb, vf2* FSa, vf2* FSb) {
;     ...
;         for (int j = 0; j < N / NTHR; ++j) { const int i = tid + NTHR * j; if (i < L) { va[j] = hfa[i]; vb[j] = hfb[i]; } else if (i == L) { va[j] = 0.f; vb[j] = 0.f; } else { va[j] = hba[N - i]; vb[j] = hbb[N - i]; } }
.LBB0_2790:
	s_andn2_saveexec_b64 s[0:1], s[0:1]
	s_cbranch_execz .LBB0_2792
	v_ashrrev_i32_e32 v73, 31, v72
	v_lshlrev_b64 v[74:75], 2, v[72:73]
	v_lshl_add_u64 v[76:77], s[4:5], 0, v[74:75]
	v_lshl_add_u64 v[74:75], s[58:59], 0, v[74:75]
	global_load_dword v4, v[76:77], off
	s_nop 0
	global_load_dword v75, v[74:75], off

; template <int M>
; __device__ __forceinline__ void hy_filter_spectra(LAS vf2* X, const int tid_in, const float* hfa, const float* hba, const float* hfb, const float* hbb, vf2* FSa, vf2* FSb) {
;     ...
;         for (int j = 0; j < N / NTHR; ++j) { const int i = tid + NTHR * j; if (i < L) { va[j] = hfa[i]; vb[j] = hfb[i]; } else if (i == L) { va[j] = 0.f; vb[j] = 0.f; } else { va[j] = hba[N - i]; vb[j] = hbb[N - i]; } }
.LBB0_2798:
	s_andn2_saveexec_b64 s[0:1], s[0:1]
	s_cbranch_execz .LBB0_2800
	v_ashrrev_i32_e32 v77, 31, v76
	v_lshlrev_b64 v[78:79], 2, v[76:77]
	v_lshl_add_u64 v[80:81], s[4:5], 0, v[78:79]
	v_lshl_add_u64 v[78:79], s[58:59], 0, v[78:79]
	global_load_dword v5, v[80:81], off
	s_nop 0
	global_load_dword v79, v[78:79], off

; template <int M>
; __device__ __forceinline__ void hy_filter_spectra(LAS vf2* X, const int tid_in, const float* hfa, const float* hba, const float* hfb, const float* hbb, vf2* FSa, vf2* FSb) {
;     ...
;         for (int j = 0; j < N / NTHR; ++j) { const int i = tid + NTHR * j; if (i < L) { va[j] = hfa[i]; vb[j] = hfb[i]; } else if (i == L) { va[j] = 0.f; vb[j] = 0.f; } else { va[j] = hba[N - i]; vb[j] = hbb[N - i]; } }
.LBB0_2806:
	s_andn2_saveexec_b64 s[0:1], s[0:1]
	s_cbranch_execz .LBB0_2808
	v_ashrrev_i32_e32 v81, 31, v80
	v_lshlrev_b64 v[82:83], 2, v[80:81]
	v_lshl_add_u64 v[84:85], s[4:5], 0, v[82:83]
	v_lshl_add_u64 v[82:83], s[58:59], 0, v[82:83]
	global_load_dword v6, v[84:85], off
	s_nop 0
	global_load_dword v83, v[82:83], off

; template <int M>
; __device__ __forceinline__ void hy_filter_spectra(LAS vf2* X, const int tid_in, const float* hfa, const float* hba, const float* hfb, const float* hbb, vf2* FSa, vf2* FSb) {
;     ...
;         for (int j = 0; j < N / NTHR; ++j) { const int i = tid + NTHR * j; if (i < L) { va[j] = hfa[i]; vb[j] = hfb[i]; } else if (i == L) { va[j] = 0.f; vb[j] = 0.f; } else { va[j] = hba[N - i]; vb[j] = hbb[N - i]; } }
.LBB0_2814:
	s_andn2_saveexec_b64 s[0:1], s[0:1]
	s_cbranch_execz .LBB0_2816
	v_ashrrev_i32_e32 v85, 31, v84
	v_lshlrev_b64 v[86:87], 2, v[84:85]
	v_lshl_add_u64 v[88:89], s[4:5], 0, v[86:87]
	v_lshl_add_u64 v[86:87], s[58:59], 0, v[86:87]
	global_load_dword v7, v[88:89], off
	s_nop 0
	global_load_dword v87, v[86:87], off

; template <int M>
; __device__ __forceinline__ void hy_filter_spectra(LAS vf2* X, const int tid_in, const float* hfa, const float* hba, const float* hfb, const float* hbb, vf2* FSa, vf2* FSb) {
;     ...
;         for (int j = 0; j < N / NTHR; ++j) { const int i = tid + NTHR * j; if (i < L) { va[j] = hfa[i]; vb[j] = hfb[i]; } else if (i == L) { va[j] = 0.f; vb[j] = 0.f; } else { va[j] = hba[N - i]; vb[j] = hbb[N - i]; } }
.LBB0_2822:
	s_andn2_saveexec_b64 s[0:1], s[0:1]
	s_cbranch_execz .LBB0_2824
	v_ashrrev_i32_e32 v89, 31, v88
	v_lshlrev_b64 v[90:91], 2, v[88:89]
	v_lshl_add_u64 v[92:93], s[4:5], 0, v[90:91]
	v_lshl_add_u64 v[90:91], s[58:59], 0, v[90:91]
	global_load_dword v8, v[92:93], off
	s_nop 0
	global_load_dword v91, v[90:91], off

; template <int M>
; __device__ __forceinline__ void hy_filter_spectra(LAS vf2* X, const int tid_in, const float* hfa, const float* hba, const float* hfb, const float* hbb, vf2* FSa, vf2* FSb) {
;     ...
;         for (int j = 0; j < N / NTHR; ++j) { const int i = tid + NTHR * j; if (i < L) { va[j] = hfa[i]; vb[j] = hfb[i]; } else if (i == L) { va[j] = 0.f; vb[j] = 0.f; } else { va[j] = hba[N - i]; vb[j] = hbb[N - i]; } }
.LBB0_2830:
	s_andn2_saveexec_b64 s[0:1], s[0:1]
	s_cbranch_execz .LBB0_2832
	v_ashrrev_i32_e32 v93, 31, v92
	v_lshlrev_b64 v[94:95], 2, v[92:93]
	v_lshl_add_u64 v[96:97], s[4:5], 0, v[94:95]
	v_lshl_add_u64 v[94:95], s[58:59], 0, v[94:95]
	global_load_dword v9, v[96:97], off
	s_nop 0
	global_load_dword v95, v[94:95], off

; template <int M>
; __device__ __forceinline__ void hy_filter_spectra(LAS vf2* X, const int tid_in, const float* hfa, const float* hba, const float* hfb, const float* hbb, vf2* FSa, vf2* FSb) {
;     ...
;         for (int j = 0; j < N / NTHR; ++j) { const int i = tid + NTHR * j; if (i < L) { va[j] = hfa[i]; vb[j] = hfb[i]; } else if (i == L) { va[j] = 0.f; vb[j] = 0.f; } else { va[j] = hba[N - i]; vb[j] = hbb[N - i]; } }
.LBB0_2838:
	s_andn2_saveexec_b64 s[0:1], s[0:1]
	s_cbranch_execz .LBB0_2840
	v_ashrrev_i32_e32 v97, 31, v96
	v_lshlrev_b64 v[98:99], 2, v[96:97]
	v_lshl_add_u64 v[100:101], s[4:5], 0, v[98:99]
	v_lshl_add_u64 v[98:99], s[58:59], 0, v[98:99]
	global_load_dword v10, v[100:101], off
	s_nop 0
	global_load_dword v99, v[98:99], off

; template <int M>
; __device__ __forceinline__ void hy_filter_spectra(LAS vf2* X, const int tid_in, const float* hfa, const float* hba, const float* hfb, const float* hbb, vf2* FSa, vf2* FSb) {
;     ...
;         for (int j = 0; j < N / NTHR; ++j) { const int i = tid + NTHR * j; if (i < L) { va[j] = hfa[i]; vb[j] = hfb[i]; } else if (i == L) { va[j] = 0.f; vb[j] = 0.f; } else { va[j] = hba[N - i]; vb[j] = hbb[N - i]; } }
.LBB0_2846:
	s_andn2_saveexec_b64 s[0:1], s[0:1]
	s_cbranch_execz .LBB0_2848
	v_ashrrev_i32_e32 v101, 31, v100
	v_lshlrev_b64 v[102:103], 2, v[100:101]
	v_lshl_add_u64 v[104:105], s[4:5], 0, v[102:103]
	v_lshl_add_u64 v[102:103], s[58:59], 0, v[102:103]
	global_load_dword v11, v[104:105], off
	s_nop 0
	global_load_dword v103, v[102:103], off

; template <int M>
; __device__ __forceinline__ void hy_filter_spectra(LAS vf2* X, const int tid_in, const float* hfa, const float* hba, const float* hfb, const float* hbb, vf2* FSa, vf2* FSb) {
;     ...
;         for (int j = 0; j < N / NTHR; ++j) { const int i = tid + NTHR * j; if (i < L) { va[j] = hfa[i]; vb[j] = hfb[i]; } else if (i == L) { va[j] = 0.f; vb[j] = 0.f; } else { va[j] = hba[N - i]; vb[j] = hbb[N - i]; } }
.LBB0_2854:
	s_andn2_saveexec_b64 s[0:1], s[0:1]
	s_cbranch_execz .LBB0_2856
	v_ashrrev_i32_e32 v105, 31, v104
	v_lshlrev_b64 v[106:107], 2, v[104:105]
	v_lshl_add_u64 v[108:109], s[4:5], 0, v[106:107]
	v_lshl_add_u64 v[106:107], s[58:59], 0, v[106:107]
	global_load_dword v12, v[108:109], off
	s_nop 0
	global_load_dword v107, v[106:107], off

; template <int M>
; __device__ __forceinline__ void hy_filter_spectra(LAS vf2* X, const int tid_in, const float* hfa, const float* hba, const float* hfb, const float* hbb, vf2* FSa, vf2* FSb) {
;     ...
;         for (int j = 0; j < N / NTHR; ++j) { const int i = tid + NTHR * j; if (i < L) { va[j] = hfa[i]; vb[j] = hfb[i]; } else if (i == L) { va[j] = 0.f; vb[j] = 0.f; } else { va[j] = hba[N - i]; vb[j] = hbb[N - i]; } }
.LBB0_2862:
	s_andn2_saveexec_b64 s[0:1], s[0:1]
	s_cbranch_execz .LBB0_2864
	v_ashrrev_i32_e32 v109, 31, v108
	v_lshlrev_b64 v[110:111], 2, v[108:109]
	v_lshl_add_u64 v[112:113], s[4:5], 0, v[110:111]
	v_lshl_add_u64 v[110:111], s[58:59], 0, v[110:111]
	global_load_dword v13, v[112:113], off
	s_nop 0
	global_load_dword v111, v[110:111], off

; template <int M>
; __device__ __forceinline__ void hy_filter_spectra(LAS vf2* X, const int tid_in, const float* hfa, const float* hba, const float* hfb, const float* hbb, vf2* FSa, vf2* FSb) {
;     ...
;         for (int j = 0; j < N / NTHR; ++j) { const int i = tid + NTHR * j; if (i < L) { va[j] = hfa[i]; vb[j] = hfb[i]; } else if (i == L) { va[j] = 0.f; vb[j] = 0.f; } else { va[j] = hba[N - i]; vb[j] = hbb[N - i]; } }
.LBB0_2870:
	s_andn2_saveexec_b64 s[0:1], s[0:1]
	s_cbranch_execz .LBB0_2872
	v_ashrrev_i32_e32 v113, 31, v112
	v_lshlrev_b64 v[114:115], 2, v[112:113]
	v_lshl_add_u64 v[116:117], s[4:5], 0, v[114:115]
	v_lshl_add_u64 v[114:115], s[58:59], 0, v[114:115]
	global_load_dword v14, v[116:117], off
	s_nop 0
	global_load_dword v115, v[114:115], off

; template <int M>
; __device__ __forceinline__ void hy_filter_spectra(LAS vf2* X, const int tid_in, const float* hfa, const float* hba, const float* hfb, const float* hbb, vf2* FSa, vf2* FSb) {
;     ...
;         for (int j = 0; j < N / NTHR; ++j) { const int i = tid + NTHR * j; if (i < L) { va[j] = hfa[i]; vb[j] = hfb[i]; } else if (i == L) { va[j] = 0.f; vb[j] = 0.f; } else { va[j] = hba[N - i]; vb[j] = hbb[N - i]; } }
.LBB0_2878:
	s_andn2_saveexec_b64 s[0:1], s[0:1]
	s_cbranch_execz .LBB0_2880
	v_ashrrev_i32_e32 v117, 31, v116
	v_lshlrev_b64 v[118:119], 2, v[116:117]
	v_lshl_add_u64 v[120:121], s[4:5], 0, v[118:119]
	v_lshl_add_u64 v[118:119], s[58:59], 0, v[118:119]
	global_load_dword v15, v[120:121], off
	s_nop 0
	global_load_dword v119, v[118:119], off

; template <int M>
; __device__ __forceinline__ void hy_filter_spectra(LAS vf2* X, const int tid_in, const float* hfa, const float* hba, const float* hfb, const float* hbb, vf2* FSa, vf2* FSb) {
;     ...
;         for (int j = 0; j < N / NTHR; ++j) { const int i = tid + NTHR * j; if (i < L) { va[j] = hfa[i]; vb[j] = hfb[i]; } else if (i == L) { va[j] = 0.f; vb[j] = 0.f; } else { va[j] = hba[N - i]; vb[j] = hbb[N - i]; } }
.LBB0_2886:
	s_or_saveexec_b64 s[0:1], s[0:1]
	v_add_u32_e32 v122, 0x2000, v60
	s_xor_b64 exec, exec, s[0:1]
	s_cbranch_execz .LBB0_2888
	v_ashrrev_i32_e32 v123, 31, v122
	v_lshlrev_b64 v[120:121], 2, v[122:123]
	v_lshl_add_u64 v[124:125], s[4:5], 0, v[120:121]
	v_lshl_add_u64 v[120:121], s[58:59], 0, v[120:121]
	global_load_dword v16, v[124:125], off
	s_nop 0
	global_load_dword v121, v[120:121], off

; template <int M>
; __device__ __forceinline__ void hy_filter_spectra(LAS vf2* X, const int tid_in, const float* hfa, const float* hba, const float* hfb, const float* hbb, vf2* FSa, vf2* FSb) {
;     ...
;         for (int j = 0; j < N / NTHR; ++j) { const int i = tid + NTHR * j; if (i < L) { va[j] = hfa[i]; vb[j] = hfb[i]; } else if (i == L) { va[j] = 0.f; vb[j] = 0.f; } else { va[j] = hba[N - i]; vb[j] = hbb[N - i]; } }
.LBB0_2894:
	s_andn2_saveexec_b64 s[0:1], s[0:1]
	s_cbranch_execz .LBB0_2896
	v_ashrrev_i32_e32 v125, 31, v124
	v_lshlrev_b64 v[126:127], 2, v[124:125]
	v_lshl_add_u64 v[128:129], s[4:5], 0, v[126:127]
	v_lshl_add_u64 v[126:127], s[58:59], 0, v[126:127]
	global_load_dword v17, v[128:129], off
	s_nop 0
	global_load_dword v127, v[126:127], off

; template <int M>
; __device__ __forceinline__ void hy_filter_spectra(LAS vf2* X, const int tid_in, const float* hfa, const float* hba, const float* hfb, const float* hbb, vf2* FSa, vf2* FSb) {
;     ...
;         for (int j = 0; j < N / NTHR; ++j) { const int i = tid + NTHR * j; if (i < L) { va[j] = hfa[i]; vb[j] = hfb[i]; } else if (i == L) { va[j] = 0.f; vb[j] = 0.f; } else { va[j] = hba[N - i]; vb[j] = hbb[N - i]; } }
.LBB0_2902:
	s_andn2_saveexec_b64 s[0:1], s[0:1]
	s_cbranch_execz .LBB0_2904
	v_ashrrev_i32_e32 v129, 31, v128
	v_lshlrev_b64 v[130:131], 2, v[128:129]
	v_lshl_add_u64 v[132:133], s[4:5], 0, v[130:131]
	v_lshl_add_u64 v[130:131], s[58:59], 0, v[130:131]
	global_load_dword v18, v[132:133], off
	s_nop 0
	global_load_dword v131, v[130:131], off

; template <int M>
; __device__ __forceinline__ void hy_filter_spectra(LAS vf2* X, const int tid_in, const float* hfa, const float* hba, const float* hfb, const float* hbb, vf2* FSa, vf2* FSb) {
;     ...
;         for (int j = 0; j < N / NTHR; ++j) { const int i = tid + NTHR * j; if (i < L) { va[j] = hfa[i]; vb[j] = hfb[i]; } else if (i == L) { va[j] = 0.f; vb[j] = 0.f; } else { va[j] = hba[N - i]; vb[j] = hbb[N - i]; } }
.LBB0_2910:
	s_andn2_saveexec_b64 s[0:1], s[0:1]
	s_cbranch_execz .LBB0_2912
	v_ashrrev_i32_e32 v133, 31, v132
	v_lshlrev_b64 v[134:135], 2, v[132:133]
	v_lshl_add_u64 v[136:137], s[4:5], 0, v[134:135]
	v_lshl_add_u64 v[134:135], s[58:59], 0, v[134:135]
	global_load_dword v19, v[136:137], off
	s_nop 0
	global_load_dword v135, v[134:135], off

; template <int M>
; __device__ __forceinline__ void hy_filter_spectra(LAS vf2* X, const int tid_in, const float* hfa, const float* hba, const float* hfb, const float* hbb, vf2* FSa, vf2* FSb) {
;     ...
;         for (int j = 0; j < N / NTHR; ++j) { const int i = tid + NTHR * j; if (i < L) { va[j] = hfa[i]; vb[j] = hfb[i]; } else if (i == L) { va[j] = 0.f; vb[j] = 0.f; } else { va[j] = hba[N - i]; vb[j] = hbb[N - i]; } }
.LBB0_2918:
	s_andn2_saveexec_b64 s[0:1], s[0:1]
	s_cbranch_execz .LBB0_2920
	v_ashrrev_i32_e32 v137, 31, v136
	v_lshlrev_b64 v[138:139], 2, v[136:137]
	v_lshl_add_u64 v[140:141], s[4:5], 0, v[138:139]
	v_lshl_add_u64 v[138:139], s[58:59], 0, v[138:139]
	global_load_dword v20, v[140:141], off
	s_nop 0
	global_load_dword v139, v[138:139], off

; template <int M>
; __device__ __forceinline__ void hy_filter_spectra(LAS vf2* X, const int tid_in, const float* hfa, const float* hba, const float* hfb, const float* hbb, vf2* FSa, vf2* FSb) {
;     ...
;         for (int j = 0; j < N / NTHR; ++j) { const int i = tid + NTHR * j; if (i < L) { va[j] = hfa[i]; vb[j] = hfb[i]; } else if (i == L) { va[j] = 0.f; vb[j] = 0.f; } else { va[j] = hba[N - i]; vb[j] = hbb[N - i]; } }
.LBB0_2926:
	s_andn2_saveexec_b64 s[0:1], s[0:1]
	s_cbranch_execz .LBB0_2928
	v_ashrrev_i32_e32 v141, 31, v140
	v_lshlrev_b64 v[142:143], 2, v[140:141]
	v_lshl_add_u64 v[144:145], s[4:5], 0, v[142:143]
	v_lshl_add_u64 v[142:143], s[58:59], 0, v[142:143]
	global_load_dword v21, v[144:145], off
	s_nop 0
	global_load_dword v143, v[142:143], off

; template <int M>
; __device__ __forceinline__ void hy_filter_spectra(LAS vf2* X, const int tid_in, const float* hfa, const float* hba, const float* hfb, const float* hbb, vf2* FSa, vf2* FSb) {
;     ...
;         for (int j = 0; j < N / NTHR; ++j) { const int i = tid + NTHR * j; if (i < L) { va[j] = hfa[i]; vb[j] = hfb[i]; } else if (i == L) { va[j] = 0.f; vb[j] = 0.f; } else { va[j] = hba[N - i]; vb[j] = hbb[N - i]; } }
.LBB0_2934:
	s_andn2_saveexec_b64 s[0:1], s[0:1]
	s_cbranch_execz .LBB0_2936
	v_ashrrev_i32_e32 v145, 31, v144
	v_lshlrev_b64 v[146:147], 2, v[144:145]
	v_lshl_add_u64 v[148:149], s[4:5], 0, v[146:147]
	v_lshl_add_u64 v[146:147], s[58:59], 0, v[146:147]
	global_load_dword v22, v[148:149], off
	s_nop 0
	global_load_dword v147, v[146:147], off

; template <int M>
; __device__ __forceinline__ void hy_filter_spectra(LAS vf2* X, const int tid_in, const float* hfa, const float* hba, const float* hfb, const float* hbb, vf2* FSa, vf2* FSb) {
;     ...
;         for (int j = 0; j < N / NTHR; ++j) { const int i = tid + NTHR * j; if (i < L) { va[j] = hfa[i]; vb[j] = hfb[i]; } else if (i == L) { va[j] = 0.f; vb[j] = 0.f; } else { va[j] = hba[N - i]; vb[j] = hbb[N - i]; } }
.LBB0_2942:
	s_andn2_saveexec_b64 s[0:1], s[0:1]
	s_cbranch_execz .LBB0_2944
	v_ashrrev_i32_e32 v149, 31, v148
	v_lshlrev_b64 v[150:151], 2, v[148:149]
	v_lshl_add_u64 v[152:153], s[4:5], 0, v[150:151]
	v_lshl_add_u64 v[150:151], s[58:59], 0, v[150:151]
	global_load_dword v23, v[152:153], off
	s_nop 0
	global_load_dword v151, v[150:151], off

; template <int M>
; __device__ __forceinline__ void hy_filter_spectra(LAS vf2* X, const int tid_in, const float* hfa, const float* hba, const float* hfb, const float* hbb, vf2* FSa, vf2* FSb) {
;     ...
;         for (int j = 0; j < N / NTHR; ++j) { const int i = tid + NTHR * j; if (i < L) { va[j] = hfa[i]; vb[j] = hfb[i]; } else if (i == L) { va[j] = 0.f; vb[j] = 0.f; } else { va[j] = hba[N - i]; vb[j] = hbb[N - i]; } }
.LBB0_2950:
	s_andn2_saveexec_b64 s[0:1], s[0:1]
	s_cbranch_execz .LBB0_2952
	v_ashrrev_i32_e32 v153, 31, v152
	v_lshlrev_b64 v[154:155], 2, v[152:153]
	v_lshl_add_u64 v[156:157], s[4:5], 0, v[154:155]
	v_lshl_add_u64 v[154:155], s[58:59], 0, v[154:155]
	global_load_dword v24, v[156:157], off
	s_nop 0
	global_load_dword v155, v[154:155], off

; template <int M>
; __device__ __forceinline__ void hy_filter_spectra(LAS vf2* X, const int tid_in, const float* hfa, const float* hba, const float* hfb, const float* hbb, vf2* FSa, vf2* FSb) {
;     ...
;         for (int j = 0; j < N / NTHR; ++j) { const int i = tid + NTHR * j; if (i < L) { va[j] = hfa[i]; vb[j] = hfb[i]; } else if (i == L) { va[j] = 0.f; vb[j] = 0.f; } else { va[j] = hba[N - i]; vb[j] = hbb[N - i]; } }
.LBB0_2958:
	s_andn2_saveexec_b64 s[0:1], s[0:1]
	s_cbranch_execz .LBB0_2960
	v_ashrrev_i32_e32 v157, 31, v156
	v_lshlrev_b64 v[158:159], 2, v[156:157]
	v_lshl_add_u64 v[160:161], s[4:5], 0, v[158:159]
	v_lshl_add_u64 v[158:159], s[58:59], 0, v[158:159]
	global_load_dword v25, v[160:161], off
	s_nop 0
	global_load_dword v159, v[158:159], off

; template <int M>
; __device__ __forceinline__ void hy_filter_spectra(LAS vf2* X, const int tid_in, const float* hfa, const float* hba, const float* hfb, const float* hbb, vf2* FSa, vf2* FSb) {
;     ...
;         for (int j = 0; j < N / NTHR; ++j) { const int i = tid + NTHR * j; if (i < L) { va[j] = hfa[i]; vb[j] = hfb[i]; } else if (i == L) { va[j] = 0.f; vb[j] = 0.f; } else { va[j] = hba[N - i]; vb[j] = hbb[N - i]; } }
.LBB0_3070:
	s_andn2_saveexec_b64 s[56:57], s[56:57]
	s_cbranch_execz .LBB0_3072
	v_ashrrev_i32_e32 v27, 31, v26
	v_lshlrev_b64 v[30:31], 2, v[26:27]
	v_lshl_add_u64 v[32:33], s[0:1], 0, v[30:31]
	v_lshl_add_u64 v[30:31], s[2:3], 0, v[30:31]
	global_load_dword v1, v[32:33], off offset:2048
	s_nop 0
	global_load_dword v31, v[30:31], off offset:2048

; template <int M>
; __device__ __forceinline__ void hy_filter_spectra(LAS vf2* X, const int tid_in, const float* hfa, const float* hba, const float* hfb, const float* hbb, vf2* FSa, vf2* FSb) {
;     ...
;         for (int j = 0; j < N / NTHR; ++j) { const int i = tid + NTHR * j; if (i < L) { va[j] = hfa[i]; vb[j] = hfb[i]; } else if (i == L) { va[j] = 0.f; vb[j] = 0.f; } else { va[j] = hba[N - i]; vb[j] = hbb[N - i]; } }
.LBB0_3086:
	s_andn2_saveexec_b64 s[56:57], s[56:57]
	s_cbranch_execz .LBB0_3088
	v_ashrrev_i32_e32 v35, 31, v34
	v_lshlrev_b64 v[36:37], 2, v[34:35]
	v_lshl_add_u64 v[38:39], s[0:1], 0, v[36:37]
	v_lshl_add_u64 v[36:37], s[2:3], 0, v[36:37]
	global_load_dword v3, v[38:39], off
	s_nop 0
	global_load_dword v37, v[36:37], off
